# sample attention: rope-part sum of squares computed once per token at staging (8-lane DPP reduce of the f32 values) instead of per wave from the bf16 tile
# speedup vs baseline: 1.0076x; 1.0068x over previous
.LBB0_1599:
	s_or_b64 exec, exec, s[0:1]
	s_waitcnt vmcnt(0)
	v_readlane_b32 s0, v227, 0
	s_ashr_i32 s1, s0, 31
	s_lshl_b32 s39, s2, 6
	s_lshl_b64 s[2:3], s[0:1], 17
	v_lshl_add_u64 v[0:1], v[182:183], 0, s[2:3]
	v_add_co_u32_e32 v2, vcc, 0x2000, v0
	s_lshl_b64 s[2:3], s[0:1], 14
	s_nop 0
	v_addc_co_u32_e32 v3, vcc, 0, v1, vcc
	global_load_dwordx4 v[24:27], v[0:1], off nt
	global_load_dwordx4 v[20:23], v[2:3], off nt
	v_add_co_u32_e32 v2, vcc, 0x4000, v0
	s_lshl_b64 s[0:1], s[0:1], 7
	s_nop 0
	v_addc_co_u32_e32 v3, vcc, 0, v1, vcc
	v_add_co_u32_e32 v4, vcc, 0x6000, v0
	s_or_b32 s0, s0, 64
	s_nop 0
	v_addc_co_u32_e32 v5, vcc, 0, v1, vcc
	global_load_dwordx4 v[28:31], v[2:3], off nt
	global_load_dwordx4 v[12:15], v[4:5], off nt
	v_add_co_u32_e32 v2, vcc, 0x8000, v0
	v_mov_b32_e32 v180, v181
	s_nop 0
	v_addc_co_u32_e32 v3, vcc, 0, v1, vcc
	v_add_co_u32_e32 v4, vcc, 0xa000, v0
	v_add_u32_e32 v228, 0x18f00, v212
	s_nop 0
	v_addc_co_u32_e32 v5, vcc, 0, v1, vcc
	global_load_dwordx4 v[186:189], v[2:3], off nt
	global_load_dwordx4 v[8:11], v[4:5], off nt
	v_add_co_u32_e32 v2, vcc, 0xc000, v0
	s_mov_b32 s40, 0
	s_nop 0
	v_addc_co_u32_e32 v3, vcc, 0, v1, vcc
	v_add_co_u32_e32 v0, vcc, 0xe000, v0
	s_mov_b32 s41, 1
	s_nop 0
	v_addc_co_u32_e32 v1, vcc, 0, v1, vcc
	global_load_dwordx4 v[16:19], v[2:3], off nt
	global_load_dwordx4 v[4:7], v[0:1], off nt
	v_lshl_add_u64 v[0:1], v[184:185], 0, s[2:3]
	s_lshl_b64 s[2:3], s[0:1], 10
	v_lshl_add_u64 v[120:121], v[182:183], 0, s[2:3]
	v_add_co_u32_e32 v100, vcc, s22, v120
	s_lshl_b64 s[0:1], s[0:1], 7
	s_nop 0
	v_addc_co_u32_e32 v101, vcc, 0, v121, vcc
	v_add_co_u32_e32 v104, vcc, s24, v120
	v_lshl_add_u64 v[128:129], v[184:185], 0, s[0:1]
	s_nop 0
	v_addc_co_u32_e32 v105, vcc, 0, v121, vcc
	v_add_co_u32_e32 v108, vcc, s25, v120
	v_readlane_b32 s0, v227, 1
	s_nop 0
	v_addc_co_u32_e32 v109, vcc, 0, v121, vcc
	v_add_co_u32_e32 v112, vcc, s26, v120
	s_ashr_i32 s1, s0, 31
	s_nop 0
	v_addc_co_u32_e32 v113, vcc, 0, v121, vcc
	v_add_co_u32_e32 v116, vcc, s27, v120
	s_lshl_b64 s[2:3], s[0:1], 14
	s_nop 0
	v_addc_co_u32_e32 v117, vcc, 0, v121, vcc
	v_add_co_u32_e32 v122, vcc, s28, v120
	s_lshl_b64 s[0:1], s[0:1], 17
	s_nop 0
	v_addc_co_u32_e32 v123, vcc, 0, v121, vcc
	v_add_co_u32_e32 v124, vcc, s29, v120
	global_load_dwordx4 v[0:3], v[0:1], off nt
	s_nop 0
	v_addc_co_u32_e32 v125, vcc, 0, v121, vcc
	global_load_dwordx4 v[96:99], v[120:121], off nt
	s_nop 0
	global_load_dwordx4 v[100:103], v[100:101], off nt
	s_nop 0
	global_load_dwordx4 v[104:107], v[104:105], off nt
	s_nop 0
	global_load_dwordx4 v[108:111], v[108:109], off nt
	s_nop 0
	global_load_dwordx4 v[112:115], v[112:113], off nt
	s_nop 0
	global_load_dwordx4 v[116:119], v[116:117], off nt
	s_nop 0
	global_load_dwordx4 v[120:123], v[122:123], off nt
	s_nop 0
	global_load_dwordx4 v[124:127], v[124:125], off nt
	s_mov_b32 s42, 0
	global_load_dwordx4 v[128:131], v[128:129], off nt
	s_waitcnt vmcnt(17)
	v_cvt_pk_bf16_f32 v190, v24, v25
	v_cvt_pk_fp8_f32 v180, v24, v25
	v_lshl_add_u64 v[24:25], v[184:185], 0, s[2:3]
	s_barrier
	global_load_dwordx4 v[132:135], v[24:25], off nt
	v_lshl_add_u64 v[24:25], v[182:183], 0, s[0:1]
	v_add_co_u32_e32 v136, vcc, 0xe000, v24
	v_cvt_pk_fp8_f32 v180, v26, v27 op_sel:[0,0,1]
	s_nop 0
	v_addc_co_u32_e32 v137, vcc, 0, v25, vcc
	v_add_co_u32_e32 v138, vcc, 0xc000, v24
	v_cvt_pk_bf16_f32 v191, v26, v27
	s_nop 0
	v_addc_co_u32_e32 v139, vcc, 0, v25, vcc
	v_add_co_u32_e32 v140, vcc, 0xa000, v24
	s_waitcnt vmcnt(10)
	v_and_b32_e32 v202, 7, v168
	v_lshrrev_b32_e32 v214, 3, v168
	v_lshlrev_b32_e32 v202, 8, v202
	v_lshl_or_b32 v214, s91, 3, v214
	v_lshl_add_u32 v202, v214, 2, v202
	v_add_u32_e32 v202, 0x21700, v202
	v_mul_f32_e32 v214, v0, v0
	v_fmac_f32_e32 v214, v1, v1
	v_fmac_f32_e32 v214, v2, v2
	v_fmac_f32_e32 v214, v3, v3
	s_nop 1
	v_add_f32_dpp v214, v214, v214 quad_perm:[1,0,3,2] row_mask:0xf bank_mask:0xf
	s_nop 1
	v_add_f32_dpp v214, v214, v214 quad_perm:[2,3,0,1] row_mask:0xf bank_mask:0xf
	s_nop 1
	v_add_f32_dpp v214, v214, v214 row_half_mirror row_mask:0xf bank_mask:0xf
	v_mul_f32_e32 v214, 0.5, v214
	ds_write_b32 v202, v214
	v_lshlrev_b32_e32 v214, 2, v176
	v_add_u32_e32 v214, 0x21700, v214
	v_cvt_pk_bf16_f32 v0, v0, v1
	v_addc_co_u32_e32 v141, vcc, 0, v25, vcc
	global_load_dwordx4 v[152:155], v[138:139], off nt
	s_nop 0
	global_load_dwordx4 v[140:143], v[140:141], off nt
	v_add_co_u32_e32 v138, vcc, 0x8000, v24
	v_cvt_pk_bf16_f32 v1, v2, v3
	s_nop 0
	v_addc_co_u32_e32 v139, vcc, 0, v25, vcc
	v_add_co_u32_e32 v144, vcc, 0x6000, v24
	s_nop 1
	v_addc_co_u32_e32 v145, vcc, 0, v25, vcc
	global_load_dwordx4 v[156:159], v[138:139], off nt
	s_nop 0
	global_load_dwordx4 v[144:147], v[144:145], off nt
	v_add_co_u32_e32 v138, vcc, 0x4000, v24
	s_nop 1
	v_addc_co_u32_e32 v139, vcc, 0, v25, vcc
	v_add_co_u32_e32 v148, vcc, 0x2000, v24
	s_nop 1
	v_addc_co_u32_e32 v149, vcc, 0, v25, vcc
	global_load_dwordx4 v[160:163], v[138:139], off nt
	s_nop 0
	global_load_dwordx4 v[148:151], v[148:149], off nt
	s_nop 0
	global_load_dwordx4 v[164:167], v[136:137], off nt
	s_nop 0
	global_load_dwordx4 v[136:139], v[24:25], off nt
	v_mov_b32_e32 v24, v181
	v_cvt_pk_fp8_f32 v24, v20, v21
	v_cvt_pk_bf16_f32 v20, v20, v21
	v_cvt_pk_bf16_f32 v21, v22, v23
	ds_write_b64 v201, v[190:191]
	v_cvt_pk_fp8_f32 v24, v22, v23 op_sel:[0,0,1]
	ds_write_b32 v228, v180
	ds_write_b64 v201, v[20:21] offset:4736
	v_mov_b32_e32 v22, v181
	v_cvt_pk_bf16_f32 v20, v28, v29
	v_cvt_pk_bf16_f32 v21, v30, v31
	v_cvt_pk_fp8_f32 v22, v28, v29
	ds_write_b32 v228, v24 offset:2176
	ds_write_b64 v201, v[20:21] offset:9472
	v_mov_b32_e32 v20, v181
	v_cvt_pk_fp8_f32 v20, v12, v13
	v_cvt_pk_fp8_f32 v22, v30, v31 op_sel:[0,0,1]
	v_cvt_pk_bf16_f32 v12, v12, v13
	v_cvt_pk_bf16_f32 v13, v14, v15
	v_cvt_pk_fp8_f32 v20, v14, v15 op_sel:[0,0,1]
	ds_write_b32 v228, v22 offset:4352
	ds_write_b64 v201, v[12:13] offset:14208
	v_cvt_pk_bf16_f32 v12, v186, v187
	v_cvt_pk_bf16_f32 v13, v188, v189
	ds_write_b32 v228, v20 offset:6528
	ds_write_b64 v201, v[12:13] offset:18944
	v_mov_b32_e32 v12, v181
	v_cvt_pk_fp8_f32 v12, v8, v9
	v_mov_b32_e32 v14, v181
	v_cvt_pk_fp8_f32 v14, v186, v187
	v_cvt_pk_bf16_f32 v8, v8, v9
	v_cvt_pk_bf16_f32 v9, v10, v11
	v_cvt_pk_fp8_f32 v12, v10, v11 op_sel:[0,0,1]
	v_mov_b32_e32 v10, v181
	v_mov_b32_e32 v11, v181
	v_cvt_pk_fp8_f32 v10, v16, v17
	v_cvt_pk_fp8_f32 v11, v4, v5
	v_cvt_pk_fp8_f32 v14, v188, v189 op_sel:[0,0,1]
	v_cvt_pk_bf16_f32 v4, v4, v5
	v_cvt_pk_fp8_f32 v10, v18, v19 op_sel:[0,0,1]
	v_cvt_pk_fp8_f32 v11, v6, v7 op_sel:[0,0,1]
	ds_write_b32 v228, v14 offset:8704
	ds_write_b64 v201, v[8:9] offset:23680
	ds_write_b32 v228, v12 offset:10880
	v_cvt_pk_bf16_f32 v8, v16, v17
	v_cvt_pk_bf16_f32 v9, v18, v19
	v_cvt_pk_bf16_f32 v5, v6, v7
	ds_write_b64 v201, v[8:9] offset:28416
	ds_write_b32 v228, v10 offset:13056
	ds_write_b64 v201, v[4:5] offset:33152
	ds_write_b32 v228, v11 offset:15232
	ds_write_b64 v213, v[0:1] offset:512
	v_mov_b32_e32 v0, 0
	v_mov_b32_e32 v1, v0
	v_mov_b32_e32 v2, v0
	v_mov_b32_e32 v3, v0
	v_mov_b32_e32 v4, v0
	v_mov_b32_e32 v5, v0
	v_mov_b32_e32 v6, v0
	v_mov_b32_e32 v7, v0
	v_mov_b32_e32 v8, v0
	v_mov_b32_e32 v9, v0
	v_mov_b32_e32 v10, v0
	v_mov_b32_e32 v11, v0
	v_mov_b32_e32 v12, v0
	v_mov_b32_e32 v13, v0
	v_mov_b32_e32 v14, v0
	v_mov_b32_e32 v15, v0
	v_mov_b32_e32 v188, v0
	v_mov_b32_e32 v189, v0
	v_mov_b32_e32 v186, v0
	v_mov_b32_e32 v187, v0
	s_waitcnt vmcnt(9)
	v_cvt_pk_fp8_f32 v16, v96, v97
	v_cvt_pk_fp8_f32 v17, v100, v101
	v_cvt_pk_fp8_f32 v18, v104, v105
	v_cvt_pk_fp8_f32 v19, v108, v109
	v_cvt_pk_fp8_f32 v20, v112, v113
	v_cvt_pk_fp8_f32 v21, v116, v117
	v_cvt_pk_fp8_f32 v22, v120, v121
	v_cvt_pk_fp8_f32 v23, v124, v125
	v_cvt_pk_fp8_f32 v16, v98, v99 op_sel:[0,0,1]
	v_cvt_pk_fp8_f32 v17, v102, v103 op_sel:[0,0,1]
	v_cvt_pk_fp8_f32 v18, v106, v107 op_sel:[0,0,1]
	v_cvt_pk_fp8_f32 v19, v110, v111 op_sel:[0,0,1]
	v_cvt_pk_fp8_f32 v20, v114, v115 op_sel:[0,0,1]
	v_cvt_pk_fp8_f32 v21, v118, v119 op_sel:[0,0,1]
	v_cvt_pk_fp8_f32 v22, v122, v123 op_sel:[0,0,1]
	v_cvt_pk_fp8_f32 v23, v126, v127 op_sel:[0,0,1]
	s_nop 1
	ds_write_b32 v228, v16 offset:17408
	ds_write_b32 v228, v17 offset:19584
	ds_write_b32 v228, v18 offset:21760
	ds_write_b32 v228, v19 offset:23936
	ds_write_b32 v228, v20 offset:26112
	ds_write_b32 v228, v21 offset:28288
	ds_write_b32 v228, v22 offset:30464
	ds_write_b32 v228, v23 offset:32640
	s_branch .LBB0_1602

.LBB0_1607:
	s_or_b64 exec, exec, s[2:3]
	v_mov_b32_e32 v187, 0
	v_mov_b32_e32 v186, v187
	v_mov_b32_e32 v189, v187
	v_mov_b32_e32 v188, v187
	v_mov_b32_e32 v15, v187
	v_mov_b32_e32 v14, v187
	v_mov_b32_e32 v13, v187
	v_mov_b32_e32 v12, v187
	v_mov_b32_e32 v11, v187
	v_mov_b32_e32 v10, v187
	v_mov_b32_e32 v9, v187
	v_mov_b32_e32 v8, v187
	v_mov_b32_e32 v7, v187
	v_mov_b32_e32 v6, v187
	v_mov_b32_e32 v5, v187
	v_mov_b32_e32 v4, v187
	v_mov_b32_e32 v3, v187
	v_mov_b32_e32 v2, v187
	v_mov_b32_e32 v1, v187
	v_mov_b32_e32 v0, v187
	s_waitcnt lgkmcnt(0)
	s_barrier
	s_cmp_lg_u32 s42, 0
	s_cbranch_scc1 .LBB0_1608
	ds_read_b128 v[246:249], v207
	ds_read_b128 v[250:253], v207 offset:16
	ds_read_b128 v[24:27], v207 offset:64
	ds_read_b128 v[28:31], v207 offset:80
	s_waitcnt lgkmcnt(2)
	v_mfma_scale_f32_32x32x64_f8f6f4 v[230:245], v[32:39], v[246:253], 0, v208, v208 op_sel_hi:[0,0,0]
	ds_read_b128 v[246:249], v207 offset:128
	ds_read_b128 v[250:253], v207 offset:144
	s_waitcnt lgkmcnt(2)
	v_mfma_scale_f32_32x32x64_f8f6f4 v[230:245], v[40:47], v[24:31], v[230:245], v208, v208 op_sel_hi:[0,0,0]
	ds_read_b128 v[24:27], v207 offset:192
	ds_read_b128 v[28:31], v207 offset:208
	s_waitcnt lgkmcnt(2)
	v_mfma_scale_f32_32x32x64_f8f6f4 v[230:245], v[48:55], v[246:253], v[230:245], v208, v208 op_sel_hi:[0,0,0]
	ds_read_b128 v[246:249], v207
	ds_read_b128 v[250:253], v207 offset:16
	s_waitcnt lgkmcnt(2)
	v_mfma_scale_f32_32x32x64_f8f6f4 v[230:245], v[56:63], v[24:31], v[230:245], v208, v208 op_sel_hi:[0,0,0]
	ds_read_b128 v[24:27], v207 offset:64
	ds_read_b128 v[28:31], v207 offset:80
	s_nop 15
	s_nop 1
	v_mul_f32_e32 v180, v231, v231
	v_fmac_f32_e32 v180, v230, v230
	v_fmac_f32_e32 v180, v232, v232
	v_fmac_f32_e32 v180, v233, v233
	v_fmac_f32_e32 v180, v234, v234
	v_fmac_f32_e32 v180, v235, v235
	v_fmac_f32_e32 v180, v236, v236
	v_fmac_f32_e32 v180, v237, v237
	v_fmac_f32_e32 v180, v238, v238
	v_fmac_f32_e32 v180, v239, v239
	v_fmac_f32_e32 v180, v240, v240
	v_fmac_f32_e32 v180, v241, v241
	v_fmac_f32_e32 v180, v242, v242
	v_fmac_f32_e32 v180, v243, v243
	v_fmac_f32_e32 v180, v244, v244
	v_fmac_f32_e32 v180, v245, v245
	s_waitcnt lgkmcnt(2)
	v_mfma_scale_f32_32x32x64_f8f6f4 v[230:245], v[64:71], v[246:253], 0, v208, v208 op_sel_hi:[0,0,0]
	ds_read_b128 v[246:249], v207 offset:128
	ds_read_b128 v[250:253], v207 offset:144
	s_waitcnt lgkmcnt(2)
	v_mfma_scale_f32_32x32x64_f8f6f4 v[230:245], v[72:79], v[24:31], v[230:245], v208, v208 op_sel_hi:[0,0,0]
	ds_read_b128 v[24:27], v207 offset:192
	ds_read_b128 v[28:31], v207 offset:208
	s_waitcnt lgkmcnt(2)
	v_mfma_scale_f32_32x32x64_f8f6f4 v[230:245], v[80:87], v[246:253], v[230:245], v208, v208 op_sel_hi:[0,0,0]
	ds_read_b128 v[246:249], v207 offset:8704
	ds_read_b128 v[250:253], v207 offset:8720
	s_waitcnt lgkmcnt(2)
	v_mfma_scale_f32_32x32x64_f8f6f4 v[230:245], v[88:95], v[24:31], v[230:245], v208, v208 op_sel_hi:[0,0,0]
	ds_read_b128 v[24:27], v207 offset:8768
	ds_read_b128 v[28:31], v207 offset:8784
	s_nop 15
	s_nop 1
	v_fmac_f32_e32 v180, v230, v230
	v_fmac_f32_e32 v180, v231, v231
	v_fmac_f32_e32 v180, v232, v232
	v_fmac_f32_e32 v180, v233, v233
	v_fmac_f32_e32 v180, v234, v234
	v_fmac_f32_e32 v180, v235, v235
	v_fmac_f32_e32 v180, v236, v236
	v_fmac_f32_e32 v180, v237, v237
	v_fmac_f32_e32 v180, v238, v238
	v_fmac_f32_e32 v180, v239, v239
	v_fmac_f32_e32 v180, v240, v240
	v_fmac_f32_e32 v180, v241, v241
	v_fmac_f32_e32 v180, v242, v242
	v_fmac_f32_e32 v180, v243, v243
	v_fmac_f32_e32 v180, v244, v244
	v_fmac_f32_e32 v180, v245, v245
	s_waitcnt lgkmcnt(2)
	v_mfma_scale_f32_32x32x64_f8f6f4 v[230:245], v[32:39], v[246:253], 0, v208, v208 op_sel_hi:[0,0,0]
	ds_read_b128 v[246:249], v207 offset:8832
	ds_read_b128 v[250:253], v207 offset:8848
	s_waitcnt lgkmcnt(2)
	v_mfma_scale_f32_32x32x64_f8f6f4 v[230:245], v[40:47], v[24:31], v[230:245], v208, v208 op_sel_hi:[0,0,0]
	ds_read_b128 v[24:27], v207 offset:8896
	ds_read_b128 v[28:31], v207 offset:8912
	s_waitcnt lgkmcnt(2)
	v_mfma_scale_f32_32x32x64_f8f6f4 v[230:245], v[48:55], v[246:253], v[230:245], v208, v208 op_sel_hi:[0,0,0]
	ds_read_b128 v[246:249], v207 offset:8704
	ds_read_b128 v[250:253], v207 offset:8720
	s_waitcnt lgkmcnt(2)
	v_mfma_scale_f32_32x32x64_f8f6f4 v[230:245], v[56:63], v[24:31], v[230:245], v208, v208 op_sel_hi:[0,0,0]
	ds_read_b128 v[24:27], v207 offset:8768
	ds_read_b128 v[28:31], v207 offset:8784
	s_nop 15
	s_nop 1
	v_mul_f32_e32 v229, v231, v231
	v_fmac_f32_e32 v229, v230, v230
	v_fmac_f32_e32 v229, v232, v232
	v_fmac_f32_e32 v229, v233, v233
	v_fmac_f32_e32 v229, v234, v234
	v_fmac_f32_e32 v229, v235, v235
	v_fmac_f32_e32 v229, v236, v236
	v_fmac_f32_e32 v229, v237, v237
	v_fmac_f32_e32 v229, v238, v238
	v_fmac_f32_e32 v229, v239, v239
	v_fmac_f32_e32 v229, v240, v240
	v_fmac_f32_e32 v229, v241, v241
	v_fmac_f32_e32 v229, v242, v242
	v_fmac_f32_e32 v229, v243, v243
	v_fmac_f32_e32 v229, v244, v244
	v_fmac_f32_e32 v229, v245, v245
	s_waitcnt lgkmcnt(2)
	v_mfma_scale_f32_32x32x64_f8f6f4 v[230:245], v[64:71], v[246:253], 0, v208, v208 op_sel_hi:[0,0,0]
	ds_read_b128 v[246:249], v207 offset:8832
	ds_read_b128 v[250:253], v207 offset:8848
	s_waitcnt lgkmcnt(2)
	v_mfma_scale_f32_32x32x64_f8f6f4 v[230:245], v[72:79], v[24:31], v[230:245], v208, v208 op_sel_hi:[0,0,0]
	ds_read_b128 v[24:27], v207 offset:8896
	ds_read_b128 v[28:31], v207 offset:8912
	s_waitcnt lgkmcnt(2)
	v_mfma_scale_f32_32x32x64_f8f6f4 v[230:245], v[80:87], v[246:253], v[230:245], v208, v208 op_sel_hi:[0,0,0]
	s_waitcnt lgkmcnt(0)
	v_mfma_scale_f32_32x32x64_f8f6f4 v[230:245], v[88:95], v[24:31], v[230:245], v208, v208 op_sel_hi:[0,0,0]
	s_nop 15
	s_nop 3
	v_fmac_f32_e32 v229, v230, v230
	v_fmac_f32_e32 v229, v231, v231
	v_fmac_f32_e32 v229, v232, v232
	v_fmac_f32_e32 v229, v233, v233
	v_fmac_f32_e32 v229, v234, v234
	v_fmac_f32_e32 v229, v235, v235
	v_fmac_f32_e32 v229, v236, v236
	v_fmac_f32_e32 v229, v237, v237
	v_fmac_f32_e32 v229, v238, v238
	v_fmac_f32_e32 v229, v239, v239
	v_fmac_f32_e32 v229, v240, v240
	v_fmac_f32_e32 v229, v241, v241
	v_fmac_f32_e32 v229, v242, v242
	v_fmac_f32_e32 v229, v243, v243
	v_fmac_f32_e32 v229, v244, v244
	v_fmac_f32_e32 v229, v245, v245
	ds_read_b32 v250, v214
	ds_read_b32 v251, v214 offset:128
.LBB0_1608:
	s_waitcnt lgkmcnt(0)
	v_fmac_f32_e32 v250, 0x3b800000, v180
	v_fmac_f32_e32 v251, 0x3b800000, v229
	s_nop 1
	ds_bpermute_b32 v249, v199, v250
	ds_bpermute_b32 v248, v199, v251
.LBB0_1610:
	s_nop 0
	ds_read_b128 v[16:19], v215
	ds_read_b128 v[20:23], v216
	ds_read_b128 v[24:27], v215 offset:64
	ds_read_b128 v[28:31], v216 offset:64
	ds_read_b128 v[190:193], v215 offset:512
	s_add_i32 s43, s42, 1
	s_waitcnt lgkmcnt(5)
	v_add_f32_e32 v246, v250, v249
	v_add_f32_e32 v247, v251, v248
	v_cndmask_b32_e64 v246, v247, v246, s[6:7]
	v_fmamk_f32 v246, v246, 0x3c2aaaab, v209
	v_mul_f32_e32 v249, 0x4f800000, v246
	v_cmp_gt_f32_e32 vcc, s37, v246
	s_waitcnt lgkmcnt(3)
	v_mfma_f32_16x16x32_bf16 v[16:19], v[16:19], v[20:23], 0
	ds_read_b128 v[20:23], v215 offset:128
	ds_read_b128 v[230:233], v216 offset:128
	s_cmp_ge_u32 s43, s39
	s_nop 1
	v_cndmask_b32_e32 v246, v246, v249, vcc
	v_sqrt_f32_e32 v249, v246
	s_nop 0
	v_add_u32_e32 v250, -1, v249
	v_fma_f32 v252, -v250, v249, v246
	v_add_u32_e32 v251, 1, v249
	s_waitcnt lgkmcnt(3)
	v_mfma_f32_16x16x32_bf16 v[16:19], v[24:27], v[28:31], v[16:19]
	ds_read_b128 v[24:27], v215 offset:192
	ds_read_b128 v[28:31], v216 offset:192
	v_cmp_ge_f32_e64 s[10:11], 0, v252
	s_nop 1
	v_cndmask_b32_e64 v250, v249, v250, s[10:11]
	v_fma_f32 v249, -v251, v249, v246
	v_cmp_lt_f32_e64 s[10:11], 0, v249
	s_nop 1
	v_cndmask_b32_e64 v249, v250, v251, s[10:11]
	s_waitcnt lgkmcnt(2)
	v_mfma_f32_16x16x32_bf16 v[16:19], v[20:23], v[230:233], v[16:19]
	ds_read_b128 v[20:23], v215 offset:256
	ds_read_b128 v[230:233], v216 offset:256
	v_mul_f32_e32 v250, 0x37800000, v249
	v_cndmask_b32_e32 v249, v249, v250, vcc
	v_cmp_class_f32_e32 vcc, v246, v210
	s_nop 1
	v_cndmask_b32_e32 v246, v249, v246, vcc
	v_div_scale_f32 v249, s[10:11], v246, v246, 1.0
	v_rcp_f32_e32 v250, v249
	s_waitcnt lgkmcnt(2)
	v_mfma_f32_16x16x32_bf16 v[16:19], v[24:27], v[28:31], v[16:19]
	ds_read_b128 v[24:27], v215 offset:320
	ds_read_b128 v[28:31], v216 offset:320
	s_nop 0
	v_fma_f32 v248, -v249, v250, 1.0
	v_fmac_f32_e32 v250, v248, v250
	v_div_scale_f32 v248, vcc, 1.0, v246, 1.0
	v_mul_f32_e32 v251, v248, v250
	v_fma_f32 v253, -v249, v251, v248
	v_fmac_f32_e32 v251, v253, v250
	s_waitcnt lgkmcnt(2)
	v_mfma_f32_16x16x32_bf16 v[16:19], v[20:23], v[230:233], v[16:19]
	ds_read_b128 v[20:23], v215 offset:384
	ds_read_b128 v[230:233], v216 offset:384
	v_fma_f32 v248, -v249, v251, v248
	s_nop 0
	v_div_fmas_f32 v248, v248, v250, v251
	v_div_fixup_f32 v246, v248, v246, 1.0
	s_waitcnt lgkmcnt(2)
	v_mfma_f32_16x16x32_bf16 v[16:19], v[24:27], v[28:31], v[16:19]
	ds_read_b128 v[24:27], v215 offset:448
	ds_read_b128 v[28:31], v216 offset:448
	ds_read_b128 v[234:237], v216 offset:512
	ds_write_b32 v203, v246
	s_waitcnt lgkmcnt(0)
	s_barrier
	v_mfma_f32_16x16x32_bf16 v[16:19], v[20:23], v[230:233], v[16:19]
	ds_read_b32 v20, v217
	v_mfma_f32_16x16x32_bf16 v[16:19], v[24:27], v[28:31], v[16:19]
	v_mfma_f32_16x16x32_bf16 v[16:19], v[190:193], v[234:237], v[16:19]
	ds_read_b128 v[246:249], v211
	ds_read_b128 v[250:253], v211 offset:16
	ds_read_b128 v[24:27], v211 offset:64
	ds_read_b128 v[28:31], v211 offset:80
	s_waitcnt lgkmcnt(4)
	s_nop 6
	v_fma_f32 v16, v16, v20, -v177
	v_fma_f32 v17, v17, v20, -v177
	v_fma_f32 v18, v18, v20, -v177
	v_fma_f32 v19, v19, v20, -v177
	v_exp_f32_e32 v192, v16
	v_exp_f32_e32 v193, v17
	v_exp_f32_e32 v190, v18
	v_exp_f32_e32 v191, v19
	v_bfe_u32 v16, v192, 16, 1
	v_bfe_u32 v17, v193, 16, 1
	v_bfe_u32 v18, v190, 16, 1
	v_bfe_u32 v19, v191, 16, 1
	v_add3_u32 v16, v192, v16, s38
	v_add3_u32 v17, v193, v17, s38
	v_add3_u32 v18, v190, v18, s38
	v_add3_u32 v19, v191, v19, s38
	ds_write_b16_d16_hi v218, v16
	ds_write_b16_d16_hi v218, v17 offset:144
	ds_write_b16_d16_hi v218, v18 offset:288
	ds_write_b16_d16_hi v218, v19 offset:432
	s_cbranch_scc1 .LBB0_1613
	s_waitcnt lgkmcnt(6)
	v_mfma_scale_f32_32x32x64_f8f6f4 v[230:245], v[32:39], v[246:253], 0, v208, v208 op_sel_hi:[0,0,0]
	v_cvt_pk_bf16_f32 v16, v96, v97
	v_cvt_pk_bf16_f32 v17, v98, v99
	ds_write_b64 v201, v[16:17] offset:37888
	v_cvt_pk_bf16_f32 v18, v100, v101
	v_cvt_pk_bf16_f32 v19, v102, v103
	ds_write_b64 v201, v[18:19] offset:42624
	v_cvt_pk_bf16_f32 v20, v104, v105
	v_cvt_pk_bf16_f32 v21, v106, v107
	ds_write_b64 v201, v[20:21] offset:47360
	v_cvt_pk_bf16_f32 v22, v108, v109
	v_cvt_pk_bf16_f32 v23, v110, v111
	ds_write_b64 v201, v[22:23] offset:52096
	ds_read_b128 v[246:249], v211 offset:128
	ds_read_b128 v[250:253], v211 offset:144
	s_waitcnt lgkmcnt(10)
	v_mfma_scale_f32_32x32x64_f8f6f4 v[230:245], v[40:47], v[24:31], v[230:245], v208, v208 op_sel_hi:[0,0,0]
	v_cvt_pk_bf16_f32 v16, v112, v113
	v_cvt_pk_bf16_f32 v17, v114, v115
	ds_write_b64 v201, v[16:17] offset:56832
	v_cvt_pk_bf16_f32 v18, v116, v117
	v_cvt_pk_bf16_f32 v19, v118, v119
	ds_write_b64 v201, v[18:19] offset:61568
	v_cvt_pk_bf16_f32 v20, v120, v121
	v_cvt_pk_bf16_f32 v21, v122, v123
	ds_write_b64 v204, v[20:21] offset:28416
	v_cvt_pk_bf16_f32 v22, v124, v125
	v_cvt_pk_bf16_f32 v23, v126, v127
	ds_write_b64 v204, v[22:23] offset:33152
	ds_read_b128 v[24:27], v211 offset:192
	ds_read_b128 v[28:31], v211 offset:208
	s_waitcnt lgkmcnt(6)
	v_mfma_scale_f32_32x32x64_f8f6f4 v[230:245], v[48:55], v[246:253], v[230:245], v208, v208 op_sel_hi:[0,0,0]
	v_readlane_b32 s0, v227, s41
	s_ashr_i32 s1, s0, 31
	s_lshl_b64 s[0:1], s[0:1], 7
	s_or_b32 s0, s0, 64
	s_lshl_b64 s[2:3], s[0:1], 10
	v_lshl_add_u64 v[16:17], v[182:183], 0, s[2:3]
	v_add_co_u32_e32 v18, vcc, 0x2000, v16
	s_lshl_b64 s[0:1], s[0:1], 7
	s_nop 0
	v_addc_co_u32_e32 v19, vcc, 0, v17, vcc
	global_load_dwordx4 v[96:99], v[16:17], off nt
	global_load_dwordx4 v[100:103], v[18:19], off nt
	v_add_co_u32_e32 v18, vcc, 0x4000, v16
	s_nop 1
	v_addc_co_u32_e32 v19, vcc, 0, v17, vcc
	v_add_co_u32_e32 v20, vcc, 0x6000, v16
	s_nop 1
	v_addc_co_u32_e32 v21, vcc, 0, v17, vcc
	global_load_dwordx4 v[104:107], v[18:19], off nt
	ds_read_b128 v[246:249], v211
	ds_read_b128 v[250:253], v211 offset:16
	s_waitcnt lgkmcnt(2)
	v_mfma_scale_f32_32x32x64_f8f6f4 v[230:245], v[56:63], v[24:31], v[230:245], v208, v208 op_sel_hi:[0,0,0]
	global_load_dwordx4 v[108:111], v[20:21], off nt
	v_add_co_u32_e32 v18, vcc, 0x8000, v16
	s_nop 1
	v_addc_co_u32_e32 v19, vcc, 0, v17, vcc
	v_add_co_u32_e32 v20, vcc, 0xa000, v16
	s_nop 1
	v_addc_co_u32_e32 v21, vcc, 0, v17, vcc
	global_load_dwordx4 v[112:115], v[18:19], off nt
	global_load_dwordx4 v[116:119], v[20:21], off nt
	v_add_co_u32_e32 v18, vcc, 0xc000, v16
	s_nop 1
	v_addc_co_u32_e32 v19, vcc, 0, v17, vcc
	v_add_co_u32_e32 v16, vcc, 0xe000, v16
	s_nop 1
	v_addc_co_u32_e32 v17, vcc, 0, v17, vcc
	global_load_dwordx4 v[120:123], v[18:19], off nt
	global_load_dwordx4 v[124:127], v[16:17], off nt
	v_lshl_add_u64 v[16:17], v[184:185], 0, s[0:1]
	global_load_dwordx4 v[128:131], v[16:17], off nt
	ds_read_b128 v[24:27], v211 offset:64
	ds_read_b128 v[28:31], v211 offset:80
	v_mul_f32_e32 v180, v231, v231
	v_fmac_f32_e32 v180, v230, v230
	v_fmac_f32_e32 v180, v232, v232
	v_fmac_f32_e32 v180, v233, v233
	v_fmac_f32_e32 v180, v234, v234
	v_fmac_f32_e32 v180, v235, v235
	v_fmac_f32_e32 v180, v236, v236
	v_fmac_f32_e32 v180, v237, v237
	v_fmac_f32_e32 v180, v238, v238
	v_fmac_f32_e32 v180, v239, v239
	v_fmac_f32_e32 v180, v240, v240
	v_fmac_f32_e32 v180, v241, v241
	v_fmac_f32_e32 v180, v242, v242
	v_fmac_f32_e32 v180, v243, v243
	v_fmac_f32_e32 v180, v244, v244
	v_fmac_f32_e32 v180, v245, v245
	s_waitcnt lgkmcnt(2)
	v_mfma_scale_f32_32x32x64_f8f6f4 v[230:245], v[64:71], v[246:253], 0, v208, v208 op_sel_hi:[0,0,0]
	v_mul_f32_e32 v18, v128, v128
	v_fmac_f32_e32 v18, v129, v129
	v_fmac_f32_e32 v18, v130, v130
	v_fmac_f32_e32 v18, v131, v131
	v_cvt_pk_bf16_f32 v16, v128, v129
	v_cvt_pk_bf16_f32 v17, v130, v131
	v_add_f32_dpp v18, v18, v18 quad_perm:[1,0,3,2] row_mask:0xf bank_mask:0xf
	ds_write_b64 v213, v[16:17] offset:38400
	s_nop 0
	v_add_f32_dpp v18, v18, v18 quad_perm:[2,3,0,1] row_mask:0xf bank_mask:0xf
	s_nop 1
	v_add_f32_dpp v18, v18, v18 row_half_mirror row_mask:0xf bank_mask:0xf
	v_mul_f32_e32 v18, 0.5, v18
	ds_write_b32 v202, v18 offset:2048
	ds_read_b128 v[246:249], v211 offset:128
	ds_read_b128 v[250:253], v211 offset:144
	s_waitcnt lgkmcnt(4)
	v_mfma_scale_f32_32x32x64_f8f6f4 v[230:245], v[72:79], v[24:31], v[230:245], v208, v208 op_sel_hi:[0,0,0]
	ds_read_b128 v[24:27], v211 offset:192
	ds_read_b128 v[28:31], v211 offset:208
	s_waitcnt lgkmcnt(2)
	v_mfma_scale_f32_32x32x64_f8f6f4 v[230:245], v[80:87], v[246:253], v[230:245], v208, v208 op_sel_hi:[0,0,0]
	ds_read_b128 v[246:249], v211 offset:8704
	ds_read_b128 v[250:253], v211 offset:8720
	s_waitcnt lgkmcnt(2)
	v_mfma_scale_f32_32x32x64_f8f6f4 v[230:245], v[88:95], v[24:31], v[230:245], v208, v208 op_sel_hi:[0,0,0]
	ds_read_b128 v[24:27], v211 offset:8768
	ds_read_b128 v[28:31], v211 offset:8784
	s_nop 15
	s_nop 1
	v_fmac_f32_e32 v180, v230, v230
	v_fmac_f32_e32 v180, v231, v231
	v_fmac_f32_e32 v180, v232, v232
	v_fmac_f32_e32 v180, v233, v233
	v_fmac_f32_e32 v180, v234, v234
	v_fmac_f32_e32 v180, v235, v235
	v_fmac_f32_e32 v180, v236, v236
	v_fmac_f32_e32 v180, v237, v237
	v_fmac_f32_e32 v180, v238, v238
	v_fmac_f32_e32 v180, v239, v239
	v_fmac_f32_e32 v180, v240, v240
	v_fmac_f32_e32 v180, v241, v241
	v_fmac_f32_e32 v180, v242, v242
	v_fmac_f32_e32 v180, v243, v243
	v_fmac_f32_e32 v180, v244, v244
	v_fmac_f32_e32 v180, v245, v245
	s_waitcnt lgkmcnt(2)
	v_mfma_scale_f32_32x32x64_f8f6f4 v[230:245], v[32:39], v[246:253], 0, v208, v208 op_sel_hi:[0,0,0]
	ds_read_b128 v[246:249], v211 offset:8832
	ds_read_b128 v[250:253], v211 offset:8848
	s_waitcnt lgkmcnt(2)
	v_mfma_scale_f32_32x32x64_f8f6f4 v[230:245], v[40:47], v[24:31], v[230:245], v208, v208 op_sel_hi:[0,0,0]
	ds_read_b128 v[24:27], v211 offset:8896
	ds_read_b128 v[28:31], v211 offset:8912
	s_waitcnt lgkmcnt(2)
	v_mfma_scale_f32_32x32x64_f8f6f4 v[230:245], v[48:55], v[246:253], v[230:245], v208, v208 op_sel_hi:[0,0,0]
	ds_read_b128 v[246:249], v211 offset:8704
	ds_read_b128 v[250:253], v211 offset:8720
	s_waitcnt lgkmcnt(2)
	v_mfma_scale_f32_32x32x64_f8f6f4 v[230:245], v[56:63], v[24:31], v[230:245], v208, v208 op_sel_hi:[0,0,0]
	ds_read_b128 v[24:27], v211 offset:8768
	ds_read_b128 v[28:31], v211 offset:8784
	s_nop 15
	s_nop 1
	v_mul_f32_e32 v229, v231, v231
	v_fmac_f32_e32 v229, v230, v230
	v_fmac_f32_e32 v229, v232, v232
	v_fmac_f32_e32 v229, v233, v233
	v_fmac_f32_e32 v229, v234, v234
	v_fmac_f32_e32 v229, v235, v235
	v_fmac_f32_e32 v229, v236, v236
	v_fmac_f32_e32 v229, v237, v237
	v_fmac_f32_e32 v229, v238, v238
	v_fmac_f32_e32 v229, v239, v239
	v_fmac_f32_e32 v229, v240, v240
	v_fmac_f32_e32 v229, v241, v241
	v_fmac_f32_e32 v229, v242, v242
	v_fmac_f32_e32 v229, v243, v243
	v_fmac_f32_e32 v229, v244, v244
	v_fmac_f32_e32 v229, v245, v245
	s_waitcnt lgkmcnt(2)
	v_mfma_scale_f32_32x32x64_f8f6f4 v[230:245], v[64:71], v[246:253], 0, v208, v208 op_sel_hi:[0,0,0]
	ds_read_b128 v[246:249], v211 offset:8832
	ds_read_b128 v[250:253], v211 offset:8848
	s_waitcnt lgkmcnt(2)
	v_mfma_scale_f32_32x32x64_f8f6f4 v[230:245], v[72:79], v[24:31], v[230:245], v208, v208 op_sel_hi:[0,0,0]
	ds_read_b128 v[24:27], v211 offset:8896
	ds_read_b128 v[28:31], v211 offset:8912
	s_waitcnt lgkmcnt(2)
	v_mfma_scale_f32_32x32x64_f8f6f4 v[230:245], v[80:87], v[246:253], v[230:245], v208, v208 op_sel_hi:[0,0,0]
	s_waitcnt lgkmcnt(0)
	v_mfma_scale_f32_32x32x64_f8f6f4 v[230:245], v[88:95], v[24:31], v[230:245], v208, v208 op_sel_hi:[0,0,0]
	s_waitcnt vmcnt(9)
	v_cvt_pk_fp8_f32 v16, v136, v137
	v_cvt_pk_fp8_f32 v17, v148, v149
	v_cvt_pk_fp8_f32 v18, v160, v161
	v_cvt_pk_fp8_f32 v19, v144, v145
	v_cvt_pk_fp8_f32 v20, v156, v157
	v_cvt_pk_fp8_f32 v21, v140, v141
	v_cvt_pk_fp8_f32 v22, v152, v153
	v_cvt_pk_fp8_f32 v23, v164, v165
	v_cvt_pk_fp8_f32 v16, v138, v139 op_sel:[0,0,1]
	v_cvt_pk_fp8_f32 v17, v150, v151 op_sel:[0,0,1]
	v_cvt_pk_fp8_f32 v18, v162, v163 op_sel:[0,0,1]
	v_cvt_pk_fp8_f32 v19, v146, v147 op_sel:[0,0,1]
	v_cvt_pk_fp8_f32 v20, v158, v159 op_sel:[0,0,1]
	v_cvt_pk_fp8_f32 v21, v142, v143 op_sel:[0,0,1]
	v_cvt_pk_fp8_f32 v22, v154, v155 op_sel:[0,0,1]
	v_cvt_pk_fp8_f32 v23, v166, v167 op_sel:[0,0,1]
	s_nop 1
	ds_write_b32 v228, v16
	ds_write_b32 v228, v17 offset:2176
	ds_write_b32 v228, v18 offset:4352
	ds_write_b32 v228, v19 offset:6528
	ds_write_b32 v228, v20 offset:8704
	ds_write_b32 v228, v21 offset:10880
	ds_write_b32 v228, v22 offset:13056
	ds_write_b32 v228, v23 offset:15232
	v_fmac_f32_e32 v229, v230, v230
	v_fmac_f32_e32 v229, v231, v231
	v_fmac_f32_e32 v229, v232, v232
	v_fmac_f32_e32 v229, v233, v233
	v_fmac_f32_e32 v229, v234, v234
	v_fmac_f32_e32 v229, v235, v235
	v_fmac_f32_e32 v229, v236, v236
	v_fmac_f32_e32 v229, v237, v237
	v_fmac_f32_e32 v229, v238, v238
	v_fmac_f32_e32 v229, v239, v239
	v_fmac_f32_e32 v229, v240, v240
	v_fmac_f32_e32 v229, v241, v241
	v_fmac_f32_e32 v229, v242, v242
	v_fmac_f32_e32 v229, v243, v243
	v_fmac_f32_e32 v229, v244, v244
	v_fmac_f32_e32 v229, v245, v245
.LBB0_1613:
	s_waitcnt lgkmcnt(0)
	s_barrier
	ds_read_b32 v250, v214 offset:2048
	ds_read_b32 v251, v214 offset:2176
	ds_read_b128 v[16:19], v219
	ds_read_b64_tr_b16 v[20:21], v220
	ds_read_b64_tr_b16 v[22:23], v220 offset:2368
	ds_read_b128 v[24:27], v221
	ds_read_b64_tr_b16 v[28:29], v222
	ds_read_b64_tr_b16 v[30:31], v222 offset:2368
	ds_read_b128 v[230:233], v223
	ds_read_b64_tr_b16 v[234:235], v224
	ds_read_b64_tr_b16 v[236:237], v224 offset:2368
	s_waitcnt lgkmcnt(6)
	v_mfma_f32_32x32x16_bf16 v[0:15], v[16:19], v[20:23], v[0:15]
	ds_read_b128 v[16:19], v225
	ds_read_b64_tr_b16 v[20:21], v226
	ds_read_b64_tr_b16 v[22:23], v226 offset:2368
	s_waitcnt lgkmcnt(6)
	v_mfma_f32_32x32x16_bf16 v[0:15], v[24:27], v[28:31], v[0:15]
	s_waitcnt lgkmcnt(3)
	v_mfma_f32_32x32x16_bf16 v[0:15], v[230:233], v[234:237], v[0:15]
	s_waitcnt lgkmcnt(0)
	v_mfma_f32_32x32x16_bf16 v[0:15], v[16:19], v[20:23], v[0:15]
	v_fmac_f32_e32 v250, 0x3b800000, v180
	v_fmac_f32_e32 v251, 0x3b800000, v229
	s_nop 1
	ds_bpermute_b32 v249, v199, v250
	ds_bpermute_b32 v248, v199, v251
.LBB0_1615:
	s_nop 0
	ds_read_b128 v[16:19], v215
	ds_read_b128 v[20:23], v216 offset:37888
	ds_read_b128 v[24:27], v215 offset:64
	ds_read_b128 v[28:31], v216 offset:37952
	ds_read_b128 v[230:233], v215 offset:512
	s_add_i32 s44, s42, 2
	s_waitcnt lgkmcnt(5)
	v_add_f32_e32 v246, v250, v249
	v_add_f32_e32 v247, v251, v248
	v_cndmask_b32_e64 v246, v247, v246, s[6:7]
	v_fmamk_f32 v246, v246, 0x3c2aaaab, v209
	v_mul_f32_e32 v249, 0x4f800000, v246
	v_cmp_gt_f32_e32 vcc, s37, v246
	s_waitcnt lgkmcnt(3)
	v_mfma_f32_16x16x32_bf16 v[16:19], v[16:19], v[20:23], 0
	ds_read_b128 v[20:23], v215 offset:128
	ds_read_b128 v[234:237], v216 offset:38016
	s_cmp_ge_u32 s44, s39
	s_cselect_b64 s[0:1], -1, 0
	s_nop 1
	v_cndmask_b32_e32 v246, v246, v249, vcc
	v_sqrt_f32_e32 v249, v246
	s_nop 0
	v_add_u32_e32 v250, -1, v249
	v_fma_f32 v252, -v250, v249, v246
	v_add_u32_e32 v251, 1, v249
	s_waitcnt lgkmcnt(3)
	v_mfma_f32_16x16x32_bf16 v[16:19], v[24:27], v[28:31], v[16:19]
	ds_read_b128 v[24:27], v215 offset:192
	ds_read_b128 v[28:31], v216 offset:38080
	v_cmp_ge_f32_e64 s[10:11], 0, v252
	s_nop 1
	v_cndmask_b32_e64 v250, v249, v250, s[10:11]
	v_fma_f32 v249, -v251, v249, v246
	v_cmp_lt_f32_e64 s[10:11], 0, v249
	s_nop 1
	v_cndmask_b32_e64 v249, v250, v251, s[10:11]
	s_waitcnt lgkmcnt(2)
	v_mfma_f32_16x16x32_bf16 v[16:19], v[20:23], v[234:237], v[16:19]
	ds_read_b128 v[20:23], v215 offset:256
	ds_read_b128 v[234:237], v216 offset:38144
	v_mul_f32_e32 v250, 0x37800000, v249
	v_cndmask_b32_e32 v249, v249, v250, vcc
	v_cmp_class_f32_e32 vcc, v246, v210
	s_nop 1
	v_cndmask_b32_e32 v246, v249, v246, vcc
	v_div_scale_f32 v249, s[10:11], v246, v246, 1.0
	v_rcp_f32_e32 v250, v249
	s_waitcnt lgkmcnt(2)
	v_mfma_f32_16x16x32_bf16 v[16:19], v[24:27], v[28:31], v[16:19]
	ds_read_b128 v[24:27], v215 offset:320
	ds_read_b128 v[28:31], v216 offset:38208
	s_nop 0
	v_fma_f32 v248, -v249, v250, 1.0
	v_fmac_f32_e32 v250, v248, v250
	v_div_scale_f32 v248, vcc, 1.0, v246, 1.0
	v_mul_f32_e32 v251, v248, v250
	v_fma_f32 v253, -v249, v251, v248
	v_fmac_f32_e32 v251, v253, v250
	s_waitcnt lgkmcnt(2)
	v_mfma_f32_16x16x32_bf16 v[16:19], v[20:23], v[234:237], v[16:19]
	ds_read_b128 v[20:23], v215 offset:384
	ds_read_b128 v[234:237], v216 offset:38272
	v_fma_f32 v248, -v249, v251, v248
	s_nop 0
	v_div_fmas_f32 v248, v248, v250, v251
	v_div_fixup_f32 v246, v248, v246, 1.0
	s_waitcnt lgkmcnt(2)
	v_mfma_f32_16x16x32_bf16 v[16:19], v[24:27], v[28:31], v[16:19]
	ds_read_b128 v[24:27], v215 offset:448
	ds_read_b128 v[28:31], v216 offset:38336
	ds_read_b128 v[238:241], v216 offset:38400
	ds_write_b32 v203, v246
	s_and_b64 vcc, exec, s[0:1]
	s_waitcnt lgkmcnt(0)
	s_barrier
	v_mfma_f32_16x16x32_bf16 v[16:19], v[20:23], v[234:237], v[16:19]
	ds_read_b32 v20, v217
	v_mfma_f32_16x16x32_bf16 v[16:19], v[24:27], v[28:31], v[16:19]
	v_mfma_f32_16x16x32_bf16 v[16:19], v[230:233], v[238:241], v[16:19]
	ds_read_b128 v[246:249], v207
	ds_read_b128 v[250:253], v207 offset:16
	ds_read_b128 v[24:27], v207 offset:64
	ds_read_b128 v[28:31], v207 offset:80
	s_waitcnt lgkmcnt(4)
	s_nop 6
	v_fma_f32 v16, v16, v20, -v177
	v_fma_f32 v17, v17, v20, -v177
	v_fma_f32 v18, v18, v20, -v177
	v_fma_f32 v19, v19, v20, -v177
	v_exp_f32_e32 v16, v16
	v_exp_f32_e32 v17, v17
	v_exp_f32_e32 v18, v18
	v_exp_f32_e32 v19, v19
	v_add_f32_e32 v188, v188, v192
	v_add_f32_e32 v189, v189, v193
	v_add_f32_e32 v186, v186, v190
	v_add_f32_e32 v187, v187, v191
	v_add_f32_e32 v188, v188, v16
	v_add_f32_e32 v189, v189, v17
	v_add_f32_e32 v186, v186, v18
	v_add_f32_e32 v187, v187, v19
	v_bfe_u32 v20, v16, 16, 1
	v_bfe_u32 v21, v17, 16, 1
	v_bfe_u32 v22, v18, 16, 1
	v_bfe_u32 v23, v19, 16, 1
	v_add3_u32 v20, v16, v20, s38
	v_add3_u32 v21, v17, v21, s38
	v_add3_u32 v22, v18, v22, s38
	v_add3_u32 v23, v19, v23, s38
	ds_write_b16_d16_hi v218, v20
	ds_write_b16_d16_hi v218, v21 offset:144
	ds_write_b16_d16_hi v218, v22 offset:288
	ds_write_b16_d16_hi v218, v23 offset:432
	s_cbranch_vccnz .LBB0_1618
	s_waitcnt lgkmcnt(6)
	v_mfma_scale_f32_32x32x64_f8f6f4 v[230:245], v[32:39], v[246:253], 0, v208, v208 op_sel_hi:[0,0,0]
	v_cvt_pk_bf16_f32 v16, v136, v137
	v_cvt_pk_bf16_f32 v17, v138, v139
	ds_write_b64 v201, v[16:17] offset:0
	v_cvt_pk_bf16_f32 v18, v148, v149
	v_cvt_pk_bf16_f32 v19, v150, v151
	ds_write_b64 v201, v[18:19] offset:4736
	v_cvt_pk_bf16_f32 v20, v160, v161
	v_cvt_pk_bf16_f32 v21, v162, v163
	ds_write_b64 v201, v[20:21] offset:9472
	v_cvt_pk_bf16_f32 v22, v144, v145
	v_cvt_pk_bf16_f32 v23, v146, v147
	ds_write_b64 v201, v[22:23] offset:14208
	ds_read_b128 v[246:249], v207 offset:128
	ds_read_b128 v[250:253], v207 offset:144
	s_waitcnt lgkmcnt(10)
	v_mfma_scale_f32_32x32x64_f8f6f4 v[230:245], v[40:47], v[24:31], v[230:245], v208, v208 op_sel_hi:[0,0,0]
	v_cvt_pk_bf16_f32 v16, v156, v157
	v_cvt_pk_bf16_f32 v17, v158, v159
	ds_write_b64 v201, v[16:17] offset:18944
	v_cvt_pk_bf16_f32 v18, v140, v141
	v_cvt_pk_bf16_f32 v19, v142, v143
	ds_write_b64 v201, v[18:19] offset:23680
	v_cvt_pk_bf16_f32 v20, v152, v153
	v_cvt_pk_bf16_f32 v21, v154, v155
	ds_write_b64 v201, v[20:21] offset:28416
	v_cvt_pk_bf16_f32 v22, v164, v165
	v_cvt_pk_bf16_f32 v23, v166, v167
	ds_write_b64 v201, v[22:23] offset:33152
	ds_read_b128 v[24:27], v207 offset:192
	ds_read_b128 v[28:31], v207 offset:208
	s_waitcnt lgkmcnt(6)
	v_mfma_scale_f32_32x32x64_f8f6f4 v[230:245], v[48:55], v[246:253], v[230:245], v208, v208 op_sel_hi:[0,0,0]
	s_add_i32 s2, s41, 1
	v_readlane_b32 s2, v227, s2
	s_ashr_i32 s3, s2, 31
	s_lshl_b64 s[10:11], s[2:3], 17
	v_lshl_add_u64 v[16:17], v[182:183], 0, s[10:11]
	v_add_co_u32_e32 v18, vcc, 0x2000, v16
	s_lshl_b64 s[2:3], s[2:3], 14
	s_nop 0
	v_addc_co_u32_e32 v19, vcc, 0, v17, vcc
	global_load_dwordx4 v[136:139], v[16:17], off nt
	global_load_dwordx4 v[148:151], v[18:19], off nt
	v_add_co_u32_e32 v18, vcc, 0x4000, v16
	s_nop 1
	v_addc_co_u32_e32 v19, vcc, 0, v17, vcc
	v_add_co_u32_e32 v20, vcc, 0x6000, v16
	s_nop 1
	v_addc_co_u32_e32 v21, vcc, 0, v17, vcc
	global_load_dwordx4 v[160:163], v[18:19], off nt
	ds_read_b128 v[246:249], v207
	ds_read_b128 v[250:253], v207 offset:16
	s_waitcnt lgkmcnt(2)
	v_mfma_scale_f32_32x32x64_f8f6f4 v[230:245], v[56:63], v[24:31], v[230:245], v208, v208 op_sel_hi:[0,0,0]
	global_load_dwordx4 v[144:147], v[20:21], off nt
	v_add_co_u32_e32 v18, vcc, 0x8000, v16
	s_nop 1
	v_addc_co_u32_e32 v19, vcc, 0, v17, vcc
	v_add_co_u32_e32 v20, vcc, 0xa000, v16
	s_nop 1
	v_addc_co_u32_e32 v21, vcc, 0, v17, vcc
	global_load_dwordx4 v[156:159], v[18:19], off nt
	global_load_dwordx4 v[140:143], v[20:21], off nt
	v_add_co_u32_e32 v18, vcc, 0xc000, v16
	s_nop 1
	v_addc_co_u32_e32 v19, vcc, 0, v17, vcc
	v_add_co_u32_e32 v16, vcc, 0xe000, v16
	s_nop 1
	v_addc_co_u32_e32 v17, vcc, 0, v17, vcc
	global_load_dwordx4 v[152:155], v[18:19], off nt
	global_load_dwordx4 v[164:167], v[16:17], off nt
	v_lshl_add_u64 v[16:17], v[184:185], 0, s[2:3]
	global_load_dwordx4 v[132:135], v[16:17], off nt
	ds_read_b128 v[24:27], v207 offset:64
	ds_read_b128 v[28:31], v207 offset:80
	v_mul_f32_e32 v180, v231, v231
	v_fmac_f32_e32 v180, v230, v230
	v_fmac_f32_e32 v180, v232, v232
	v_fmac_f32_e32 v180, v233, v233
	v_fmac_f32_e32 v180, v234, v234
	v_fmac_f32_e32 v180, v235, v235
	v_fmac_f32_e32 v180, v236, v236
	v_fmac_f32_e32 v180, v237, v237
	v_fmac_f32_e32 v180, v238, v238
	v_fmac_f32_e32 v180, v239, v239
	v_fmac_f32_e32 v180, v240, v240
	v_fmac_f32_e32 v180, v241, v241
	v_fmac_f32_e32 v180, v242, v242
	v_fmac_f32_e32 v180, v243, v243
	v_fmac_f32_e32 v180, v244, v244
	v_fmac_f32_e32 v180, v245, v245
	s_waitcnt lgkmcnt(2)
	v_mfma_scale_f32_32x32x64_f8f6f4 v[230:245], v[64:71], v[246:253], 0, v208, v208 op_sel_hi:[0,0,0]
	v_mul_f32_e32 v18, v132, v132
	v_fmac_f32_e32 v18, v133, v133
	v_fmac_f32_e32 v18, v134, v134
	v_fmac_f32_e32 v18, v135, v135
	v_cvt_pk_bf16_f32 v16, v132, v133
	v_cvt_pk_bf16_f32 v17, v134, v135
	v_add_f32_dpp v18, v18, v18 quad_perm:[1,0,3,2] row_mask:0xf bank_mask:0xf
	ds_write_b64 v213, v[16:17] offset:512
	s_nop 0
	v_add_f32_dpp v18, v18, v18 quad_perm:[2,3,0,1] row_mask:0xf bank_mask:0xf
	s_nop 1
	v_add_f32_dpp v18, v18, v18 row_half_mirror row_mask:0xf bank_mask:0xf
	v_mul_f32_e32 v18, 0.5, v18
	ds_write_b32 v202, v18
	ds_read_b128 v[246:249], v207 offset:128
	ds_read_b128 v[250:253], v207 offset:144
	s_waitcnt lgkmcnt(4)
	v_mfma_scale_f32_32x32x64_f8f6f4 v[230:245], v[72:79], v[24:31], v[230:245], v208, v208 op_sel_hi:[0,0,0]
	ds_read_b128 v[24:27], v207 offset:192
	ds_read_b128 v[28:31], v207 offset:208
	s_waitcnt lgkmcnt(2)
	v_mfma_scale_f32_32x32x64_f8f6f4 v[230:245], v[80:87], v[246:253], v[230:245], v208, v208 op_sel_hi:[0,0,0]
	ds_read_b128 v[246:249], v207 offset:8704
	ds_read_b128 v[250:253], v207 offset:8720
	s_waitcnt lgkmcnt(2)
	v_mfma_scale_f32_32x32x64_f8f6f4 v[230:245], v[88:95], v[24:31], v[230:245], v208, v208 op_sel_hi:[0,0,0]
	ds_read_b128 v[24:27], v207 offset:8768
	ds_read_b128 v[28:31], v207 offset:8784
	s_nop 15
	s_nop 1
	v_fmac_f32_e32 v180, v230, v230
	v_fmac_f32_e32 v180, v231, v231
	v_fmac_f32_e32 v180, v232, v232
	v_fmac_f32_e32 v180, v233, v233
	v_fmac_f32_e32 v180, v234, v234
	v_fmac_f32_e32 v180, v235, v235
	v_fmac_f32_e32 v180, v236, v236
	v_fmac_f32_e32 v180, v237, v237
	v_fmac_f32_e32 v180, v238, v238
	v_fmac_f32_e32 v180, v239, v239
	v_fmac_f32_e32 v180, v240, v240
	v_fmac_f32_e32 v180, v241, v241
	v_fmac_f32_e32 v180, v242, v242
	v_fmac_f32_e32 v180, v243, v243
	v_fmac_f32_e32 v180, v244, v244
	v_fmac_f32_e32 v180, v245, v245
	s_waitcnt lgkmcnt(2)
	v_mfma_scale_f32_32x32x64_f8f6f4 v[230:245], v[32:39], v[246:253], 0, v208, v208 op_sel_hi:[0,0,0]
	ds_read_b128 v[246:249], v207 offset:8832
	ds_read_b128 v[250:253], v207 offset:8848
	s_waitcnt lgkmcnt(2)
	v_mfma_scale_f32_32x32x64_f8f6f4 v[230:245], v[40:47], v[24:31], v[230:245], v208, v208 op_sel_hi:[0,0,0]
	ds_read_b128 v[24:27], v207 offset:8896
	ds_read_b128 v[28:31], v207 offset:8912
	s_waitcnt lgkmcnt(2)
	v_mfma_scale_f32_32x32x64_f8f6f4 v[230:245], v[48:55], v[246:253], v[230:245], v208, v208 op_sel_hi:[0,0,0]
	ds_read_b128 v[246:249], v207 offset:8704
	ds_read_b128 v[250:253], v207 offset:8720
	s_waitcnt lgkmcnt(2)
	v_mfma_scale_f32_32x32x64_f8f6f4 v[230:245], v[56:63], v[24:31], v[230:245], v208, v208 op_sel_hi:[0,0,0]
	ds_read_b128 v[24:27], v207 offset:8768
	ds_read_b128 v[28:31], v207 offset:8784
	s_nop 15
	s_nop 1
	v_mul_f32_e32 v229, v231, v231
	v_fmac_f32_e32 v229, v230, v230
	v_fmac_f32_e32 v229, v232, v232
	v_fmac_f32_e32 v229, v233, v233
	v_fmac_f32_e32 v229, v234, v234
	v_fmac_f32_e32 v229, v235, v235
	v_fmac_f32_e32 v229, v236, v236
	v_fmac_f32_e32 v229, v237, v237
	v_fmac_f32_e32 v229, v238, v238
	v_fmac_f32_e32 v229, v239, v239
	v_fmac_f32_e32 v229, v240, v240
	v_fmac_f32_e32 v229, v241, v241
	v_fmac_f32_e32 v229, v242, v242
	v_fmac_f32_e32 v229, v243, v243
	v_fmac_f32_e32 v229, v244, v244
	v_fmac_f32_e32 v229, v245, v245
	s_waitcnt lgkmcnt(2)
	v_mfma_scale_f32_32x32x64_f8f6f4 v[230:245], v[64:71], v[246:253], 0, v208, v208 op_sel_hi:[0,0,0]
	ds_read_b128 v[246:249], v207 offset:8832
	ds_read_b128 v[250:253], v207 offset:8848
	s_waitcnt lgkmcnt(2)
	v_mfma_scale_f32_32x32x64_f8f6f4 v[230:245], v[72:79], v[24:31], v[230:245], v208, v208 op_sel_hi:[0,0,0]
	ds_read_b128 v[24:27], v207 offset:8896
	ds_read_b128 v[28:31], v207 offset:8912
	s_waitcnt lgkmcnt(2)
	v_mfma_scale_f32_32x32x64_f8f6f4 v[230:245], v[80:87], v[246:253], v[230:245], v208, v208 op_sel_hi:[0,0,0]
	s_waitcnt lgkmcnt(0)
	v_mfma_scale_f32_32x32x64_f8f6f4 v[230:245], v[88:95], v[24:31], v[230:245], v208, v208 op_sel_hi:[0,0,0]
	s_waitcnt vmcnt(9)
	v_cvt_pk_fp8_f32 v16, v96, v97
	v_cvt_pk_fp8_f32 v17, v100, v101
	v_cvt_pk_fp8_f32 v18, v104, v105
	v_cvt_pk_fp8_f32 v19, v108, v109
	v_cvt_pk_fp8_f32 v20, v112, v113
	v_cvt_pk_fp8_f32 v21, v116, v117
	v_cvt_pk_fp8_f32 v22, v120, v121
	v_cvt_pk_fp8_f32 v23, v124, v125
	v_cvt_pk_fp8_f32 v16, v98, v99 op_sel:[0,0,1]
	v_cvt_pk_fp8_f32 v17, v102, v103 op_sel:[0,0,1]
	v_cvt_pk_fp8_f32 v18, v106, v107 op_sel:[0,0,1]
	v_cvt_pk_fp8_f32 v19, v110, v111 op_sel:[0,0,1]
	v_cvt_pk_fp8_f32 v20, v114, v115 op_sel:[0,0,1]
	v_cvt_pk_fp8_f32 v21, v118, v119 op_sel:[0,0,1]
	v_cvt_pk_fp8_f32 v22, v122, v123 op_sel:[0,0,1]
	v_cvt_pk_fp8_f32 v23, v126, v127 op_sel:[0,0,1]
	s_nop 1
	ds_write_b32 v228, v16 offset:17408
	ds_write_b32 v228, v17 offset:19584
	ds_write_b32 v228, v18 offset:21760
	ds_write_b32 v228, v19 offset:23936
	ds_write_b32 v228, v20 offset:26112
	ds_write_b32 v228, v21 offset:28288
	ds_write_b32 v228, v22 offset:30464
	ds_write_b32 v228, v23 offset:32640
	v_fmac_f32_e32 v229, v230, v230
	v_fmac_f32_e32 v229, v231, v231
	v_fmac_f32_e32 v229, v232, v232
	v_fmac_f32_e32 v229, v233, v233
	v_fmac_f32_e32 v229, v234, v234
	v_fmac_f32_e32 v229, v235, v235
	v_fmac_f32_e32 v229, v236, v236
	v_fmac_f32_e32 v229, v237, v237
	v_fmac_f32_e32 v229, v238, v238
	v_fmac_f32_e32 v229, v239, v239
	v_fmac_f32_e32 v229, v240, v240
	v_fmac_f32_e32 v229, v241, v241
	v_fmac_f32_e32 v229, v242, v242
	v_fmac_f32_e32 v229, v243, v243
	v_fmac_f32_e32 v229, v244, v244
	v_fmac_f32_e32 v229, v245, v245
.LBB0_1618:
	s_waitcnt lgkmcnt(0)
	s_barrier
	ds_read_b32 v250, v214
	ds_read_b32 v251, v214 offset:128
	ds_read_b128 v[16:19], v219
	ds_read_b64_tr_b16 v[20:21], v220 offset:37888
	ds_read_b64_tr_b16 v[22:23], v220 offset:40256
	ds_read_b128 v[24:27], v221
	ds_read_b64_tr_b16 v[28:29], v222 offset:37888
	ds_read_b64_tr_b16 v[30:31], v222 offset:40256
	ds_read_b128 v[230:233], v223
	ds_read_b64_tr_b16 v[234:235], v224 offset:37888
	ds_read_b64_tr_b16 v[236:237], v224 offset:40256
	s_and_b32 s2, s43, 63
	s_cmp_eq_u32 s2, 63
	s_mov_b64 s[2:3], -1
	s_waitcnt lgkmcnt(6)
	v_mfma_f32_32x32x16_bf16 v[0:15], v[16:19], v[20:23], v[0:15]
	ds_read_b128 v[16:19], v225
	ds_read_b64_tr_b16 v[20:21], v226 offset:37888
	ds_read_b64_tr_b16 v[22:23], v226 offset:40256
	s_waitcnt lgkmcnt(6)
	v_mfma_f32_32x32x16_bf16 v[0:15], v[24:27], v[28:31], v[0:15]
	s_waitcnt lgkmcnt(3)
	v_mfma_f32_32x32x16_bf16 v[0:15], v[230:233], v[234:237], v[0:15]
	s_waitcnt lgkmcnt(0)
	v_mfma_f32_32x32x16_bf16 v[0:15], v[16:19], v[20:23], v[0:15]
	s_cbranch_scc0 .LBB0_1620
	s_andn2_b64 vcc, exec, s[2:3]
	s_cbranch_vccnz .LBB0_1601
	s_branch .LBB0_1621
